# up-GEMM ConvGLU epilogue: conv weights/bias of the next unit brought into LDS by LDS-DMA at the previous epilogue start, read via ds_read_b128 (removes exposed global-load wait per unit)
# speedup vs baseline: 1.0074x; 1.0018x over previous
; #define PG8_LAS __attribute__((address_space(3)))
; #define PG8_STAGE(bufoff, gbase, voff) do { _Pragma("unroll") for (int _i = 0; _i < 2; ++_i) \
;         __builtin_amdgcn_global_load_lds((const unsigned*)((const char*)(gbase) + (voff)[_i]), (PG8_LAS unsigned*)(lds + (bufoff) + ldsw + _i * 8192), 16, 0, 0); } while (0)
; #define PG8_WAIT_V(n) asm volatile("s_waitcnt vmcnt(" #n ")" ::: "memory")
;     __device__ __forceinline__ void operator()(const f32x4 (&acc)[2][2][4][2], const Unit& u, int wr, int wc, int fr, int fq) const {
;         const int ch0 = u.pn * HALF + wc * 32 + 8 * fq; const bool l0 = (fr == 0), l15 = (fr == 15);
;         PG8_LAS float* xme = XB + ((wr * 4 + wc) * 4) * 32 + fq * 8;
; #pragma unroll
;         for (int ai = 0; ai < 2; ++ai) {
;             if (fr == 0)  { *(PG8_LAS f32x4*)(xme + (ai * 2 + 0) * 32) = acc[ai][1][0][0]; *(PG8_LAS f32x4*)(xme + (ai * 2 + 0) * 32 + 4) = acc[ai][1][0][1]; }
;             if (fr == 15) { *(PG8_LAS f32x4*)(xme + (ai * 2 + 1) * 32) = acc[ai][1][3][0]; *(PG8_LAS f32x4*)(xme + (ai * 2 + 1) * 32 + 4) = acc[ai][1][3][1]; }
;         }
;         asm volatile("s_waitcnt lgkmcnt(0)" ::: "memory"); __builtin_amdgcn_s_barrier(); asm volatile("" ::: "memory");
;         f32x4 w0[2], w1[2], w2[2], bb[2];
; #pragma unroll
;         for (int n = 0; n < 2; ++n) { w0[n] = *(const f32x4*)(cw + ch0 + 4 * n); w1[n] = *(const f32x4*)(cw + dff + ch0 + 4 * n); w2[n] = *(const f32x4*)(cw + 2 * dff + ch0 + 4 * n); bb[n] = *(const f32x4*)(cb + ch0 + 4 * n); }
; template <class Epi, class Sched, bool ALIGN_EPI = true>
; __device__ __forceinline__ void gemm_phase(PG8_LAS unsigned char* lds, const Gemm g, const Sched& S, const Epi& E, const int tid) {
;     ...
;     const char* cA = (const char*)g.A + (size_t)cur.pm * tstepA + (size_t)cur.grp * g.gsA + (size_t)cur.kt0 * kstep; const char* cB = (const char*)g.Bt + (size_t)cur.pn * tstepB + (size_t)cur.grp * g.gsB + (size_t)cur.kt0 * kstep;
;     S.a_ready(cur);
;     PG8_STAGE(PG8_SB(0, 0), cB, voffB); PG8_STAGE(PG8_SB(0, 1), cB + hstepB, voffB); PG8_STAGE(PG8_SA(0, 0), cA, voffA); PG8_STAGE(PG8_SA(0, 1), cA + hstepA, voffA);
;     if (wr == 1) PG8_BAR;
;     PG8_WAIT_V(2); PG8_BAR;
;     PG8_STAGE(PG8_SB(1, 0), cB + kstep, voffB); PG8_STAGE(PG8_SA(1, 0), cA + kstep, voffA); PG8_STAGE(PG8_SB(1, 1), cB + hstepB + kstep, voffB);
;     PG8_WAIT_V(6); PG8_BAR;
.LBB0_1232:
	v_readlane_b32 s16, v255, 22
	s_add_u32 s54, s0, 0x3d800000
	s_mul_i32 s15, s16, 0x10800
	s_addc_u32 s55, s1, 0
	v_readlane_b32 s17, v255, 23
	s_mov_b32 s18, s16
	s_mul_hi_u32 s11, s16, 0x10800
	s_add_u32 s4, s4, s15
	s_mul_i32 s17, s18, 0x5800
	s_addc_u32 s5, s5, s11
	s_mul_hi_u32 s16, s16, 0x5800
	s_add_u32 s6, s6, s17
	v_lshrrev_b32_e32 v20, 1, v12
	s_addc_u32 s7, s7, s16
	v_and_b32_e32 v20, 24, v20
	s_add_u32 s90, s0, 0x49740000
	v_and_b32_e32 v19, 15, v12
	v_lshlrev_b32_e32 v21, 1, v20
	v_lshlrev_b32_e32 v12, 2, v12
	s_addc_u32 s91, s1, 0
	s_and_b32 s11, s13, 3
	v_lshl_or_b32 v21, v19, 6, v21
	s_lshl_b32 s0, s12, 13
	v_and_b32_e32 v12, 32, v12
	s_add_i32 m0, s86, 0x18000
	v_lshl_add_u64 v[10:11], v[10:11], 0, s[36:37]
	s_lshl_b32 s13, s12, 6
	v_bitop3_b32 v22, v21, s0, v12 bitop3:0xde
	s_lshl_b32 s0, s11, 12
	s_waitcnt vmcnt(2)
	s_barrier
	global_load_lds_dwordx4 v[10:11], off
	v_lshl_add_u64 v[8:9], v[8:9], 0, s[36:37]
	s_add_i32 m0, s86, 0x1a000
	s_add_i32 s92, s86, 0x8000
	s_add_i32 s93, s86, 0xa000
	v_bitop3_b32 v193, v21, s0, v12 bitop3:0xde
	global_load_lds_dwordx4 v[8:9], off
	v_lshl_add_u64 v[4:5], v[4:5], 0, s[36:37]
	s_mov_b32 m0, s92
	s_add_u32 s0, s76, 0x80080
	global_load_lds_dwordx4 v[4:5], off
	v_lshl_add_u64 v[4:5], v[6:7], 0, s[36:37]
	s_mov_b32 m0, s93
	s_addc_u32 s1, s77, 0
	global_load_lds_dwordx4 v[4:5], off
	s_add_i32 m0, s86, 0x1c000
	v_lshl_add_u64 v[4:5], s[0:1], 0, v[2:3]
	global_load_lds_dwordx4 v[4:5], off
	v_lshl_add_u64 v[4:5], s[0:1], 0, v[184:185]
	s_add_i32 m0, s86, 0x1e000
	s_cmpk_lt_u32 s8, 0x100
	global_load_lds_dwordx4 v[4:5], off
	s_cselect_b64 s[56:57], -1, 0
	s_lshl_b32 s0, s12, 11
	s_lshl_b32 s1, s11, 9
	s_add_i32 s8, s13, 64
	s_cmp_gt_i32 s12, 0
	s_cselect_b64 s[58:59], -1, 0
	s_add_i32 s15, s13, -1
	s_lshr_b32 s16, s15, 4
	s_and_b32 s16, s16, 4
	s_or_b32 s16, s16, s11
	s_lshl_b32 s16, s16, 9
	s_cmp_lt_i32 s12, 3
	s_cselect_b64 s[60:61], -1, 0
	s_lshr_b32 s17, s8, 4
	s_and_b32 s17, s17, 4
	s_or_b32 s17, s17, s11
	s_lshl_b32 s17, s17, 9
	s_add_i32 s18, s13, 0x80
	s_add_i32 s19, s13, 0xc0
	s_cmp_gt_i32 s12, -2
	v_or_b32_e32 v192, s13, v19
	s_cselect_b64 s[62:63], -1, 0
	s_addk_i32 s13, 0x7f
	s_lshr_b32 s20, s13, 4
	s_and_b32 s20, s20, 4
	s_or_b32 s20, s20, s11
	s_lshl_b32 s20, s20, 9
	s_cmp_lt_i32 s12, 1
	s_cselect_b64 s[64:65], -1, 0
	s_lshr_b32 s12, s19, 4
	s_and_b32 s12, s12, 4
	v_or_b32_e32 v4, s18, v19
	s_add_i32 s18, 0, 0x20000
	s_or_b32 s12, s12, s11
	s_add_i32 s0, s18, s0
	s_lshl_b32 s12, s12, 9
	s_add_i32 s0, s0, s1
	s_add_u32 s66, s4, 0x5800
	s_addc_u32 s67, s5, 0
	s_movk_i32 s3, 0xcf
	s_add_u32 s68, s4, 0xb000
	v_cmp_eq_u32_e64 s[46:47], 0, v4
	v_cmp_eq_u32_e64 s[48:49], s3, v4
	v_lshlrev_b32_e32 v4, 2, v20
	s_addc_u32 s69, s5, 0
	s_lshl_b32 s1, s15, 1
	v_add_u32_e32 v194, s0, v4
	s_add_i32 s0, s18, s16
	s_and_b32 s1, s1, 0xffffff00
	s_add_i32 s0, s0, s1
	s_lshl_b32 s1, s8, 1
	v_add_u32_e32 v195, s0, v4
	s_add_i32 s0, s18, s17
	s_and_b32 s1, s1, 0xffffff00
	s_add_i32 s0, s0, s1
	s_lshl_b32 s1, s13, 1
	v_add_u32_e32 v196, s0, v4
	s_add_i32 s0, s18, s20
	s_and_b32 s1, s1, 0xffffff00
	s_add_i32 s0, s0, s1
	s_lshl_b32 s1, s19, 1
	v_add_u32_e32 v197, s0, v4
	s_add_i32 s0, s18, s12
	s_and_b32 s1, s1, 0xffffff00
	s_add_i32 s0, s0, s1
	v_add_u32_e32 v198, s0, v4
	v_lshlrev_b32_e32 v4, 15, v13
	v_and_b32_e32 v4, 0xffff0000, v4
	v_lshl_add_u32 v4, v14, 12, v4
	v_and_b32_e32 v5, 1, v13
	v_lshl_or_b32 v4, v5, 6, v4
	v_lshl_add_u32 v186, v15, 1, v4
	v_lshlrev_b32_e32 v4, 15, v16
	v_and_b32_e32 v4, 0xffff0000, v4
	s_waitcnt vmcnt(6)
	v_lshl_add_u32 v4, v17, 12, v4
	v_and_b32_e32 v5, 1, v16
	v_lshl_or_b32 v4, v5, 6, v4
	s_mov_b32 s94, 0
	s_mov_b32 s32, 0
	v_and_b32_e32 v227, 63, v247
	v_and_b32_e32 v228, 31, v227
	v_lshlrev_b32_e32 v228, 4, v228
	s_min_u32 s99, s72, 43
	s_lshl_b32 s99, s99, 9
	v_add_u32_e32 v228, s99, v228
	v_lshrrev_b32_e32 v229, 5, v227
	v_mul_u32_u24_e32 v229, 0x5800, v229
	v_add_u32_e32 v229, v229, v228
	v_add_u32_e32 v230, 0xb000, v228
	s_lshl_b32 s99, s32, 12
	s_add_i32 s99, s99, 0x21000
	s_mov_b32 m0, s99
	s_nop 0
	global_load_lds_dwordx4 v229, s[4:5]
	s_add_i32 m0, s99, 0x400
	s_nop 0
	global_load_lds_dwordx4 v230, s[4:5]
	s_add_i32 m0, s99, 0x800
	s_nop 0
	global_load_lds_dwordx4 v228, s[6:7]
	v_cmp_eq_u32_e64 s[38:39], 0, v19
	v_cmp_eq_u32_e64 s[40:41], 15, v19
	v_cmp_eq_u32_e64 s[42:43], 0, v192
	v_cmp_eq_u32_e64 s[44:45], s3, v192
	v_lshl_or_b32 v199, s11, 5, v20
	v_mov_b32_e32 v187, v3
	v_lshl_add_u32 v188, v18, 1, v4
	v_mov_b32_e32 v189, v3
	v_add_u32_e32 v200, 0, v22
	s_barrier
	s_branch .LBB0_1235

;     __device__ __forceinline__ void operator()(const f32x4 (&acc)[2][2][4][2], const Unit& u, int wr, int wc, int fr, int fq) const {
;     ...
;         asm volatile("s_waitcnt lgkmcnt(0)" ::: "memory"); __builtin_amdgcn_s_barrier(); asm volatile("" ::: "memory");
;         f32x4 w0[2], w1[2], w2[2], bb[2];
; #pragma unroll
;         for (int n = 0; n < 2; ++n) { w0[n] = *(const f32x4*)(cw + ch0 + 4 * n); w1[n] = *(const f32x4*)(cw + dff + ch0 + 4 * n); w2[n] = *(const f32x4*)(cw + 2 * dff + ch0 + 4 * n); bb[n] = *(const f32x4*)(cb + ch0 + 4 * n); }
.LBB0_1245:
	s_or_b64 exec, exec, s[18:19]
	v_lshl_or_b32 v190, s72, 7, v199
	v_ashrrev_i32_e32 v191, 31, v190
	v_lshlrev_b64 v[72:73], 2, v[190:191]
	s_waitcnt lgkmcnt(0)
	s_barrier
	v_lshlrev_b32_e32 v226, 2, v199
	s_lshl_b32 s99, s32, 12
	s_add_i32 s99, s99, 0x21000
	v_add_u32_e32 v226, s99, v226
	ds_read_b128 v[92:95], v226
	ds_read_b128 v[72:75], v226 offset:16
	ds_read_b128 v[96:99], v226 offset:512
	ds_read_b128 v[76:79], v226 offset:528
	ds_read_b128 v[100:103], v226 offset:1024
	ds_read_b128 v[84:87], v226 offset:1040
	ds_read_b128 v[104:107], v226 offset:2048
	ds_read_b128 v[88:91], v226 offset:2064
	s_xor_b32 s32, s32, 1
	v_and_b32_e32 v227, 63, v247
	v_and_b32_e32 v228, 31, v227
	v_lshlrev_b32_e32 v228, 4, v228
	s_min_u32 s99, s22, 43
	s_lshl_b32 s99, s99, 9
	v_add_u32_e32 v228, s99, v228
	v_lshrrev_b32_e32 v229, 5, v227
	v_mul_u32_u24_e32 v229, 0x5800, v229
	v_add_u32_e32 v229, v229, v228
	v_add_u32_e32 v230, 0xb000, v228
	s_lshl_b32 s99, s32, 12
	s_add_i32 s99, s99, 0x21000
	s_mov_b32 m0, s99
	s_nop 0
	global_load_lds_dwordx4 v229, s[4:5]
	s_add_i32 m0, s99, 0x400
	s_nop 0
	global_load_lds_dwordx4 v230, s[4:5]
	s_add_i32 m0, s99, 0x800
	s_nop 0
	global_load_lds_dwordx4 v228, s[6:7]
	v_mov_b32_e32 v164, 0
	s_andn2_b64 vcc, exec, s[58:59]
	v_mov_b32_e32 v176, 0
	v_mov_b32_e32 v177, 0
	v_mov_b32_e32 v178, 0
	v_mov_b32_e32 v179, 0
	v_mov_b32_e32 v172, 0
	v_mov_b32_e32 v173, 0
	v_mov_b32_e32 v174, 0
	v_mov_b32_e32 v175, 0
	s_cbranch_vccnz .LBB0_1247
	ds_read_b128 v[172:175], v195 offset:128
	ds_read_b128 v[176:179], v195 offset:144

;     static __device__ __forceinline__ float ror1(float v)  { return __builtin_bit_cast(float, __builtin_amdgcn_update_dpp(0, __builtin_bit_cast(int, v), 0x121, 0xf, 0xf, true)); }
;     static __device__ __forceinline__ float ror15(float v) { return __builtin_bit_cast(float, __builtin_amdgcn_update_dpp(0, __builtin_bit_cast(int, v), 0x12f, 0xf, 0xf, true)); }
;     __device__ __forceinline__ void operator()(const f32x4 (&acc)[2][2][4][2], const Unit& u, int wr, int wc, int fr, int fq) const {
;     ...
; #pragma unroll
;             for (int m = 0; m < 4; ++m) {
;                 const int row = u.pm * BM + ai * HALF + wr * 64 + m * 16 + fr;
;                 u32x4 ow; float cv[8];
; #pragma unroll
;                 for (int n = 0; n < 2; ++n)
; #pragma unroll
;                     for (int j = 0; j < 4; ++j) {
;                         const float g = acc[ai][1][m][n][j];
;                         const float tp = l15 ? ((m > 0) ? acc[ai][1][m > 0 ? m - 1 : 0][n][j] : xp[n][j]) : g;
;                         const float tn = l0  ? ((m < 3) ? acc[ai][1][m < 3 ? m + 1 : 3][n][j] : xn[n][j]) : g;
;                         const float gp = ror1(tp), gn = ror15(tn);
;                         cv[4 * n + j] = fmaf(w0[n][j], gp, fmaf(w1[n][j], g, fmaf(w2[n][j], gn, bb[n][j])));
;                     }
;                 const int tr = ai * HALF + wr * 64 + m * 16 + fr;
;                 if (tr == 0 || tr == 255) { float* sb = SB + ((size_t)(u.pm * 2 + (tr ? 1 : 0)) * 3) * dff + ch0;
; #pragma unroll
;                     for (int n = 0; n < 2; ++n) { *(f32x4*)(sb + 4 * n) = (f32x4){cv[4 * n], cv[4 * n + 1], cv[4 * n + 2], cv[4 * n + 3]}; *(f32x4*)(sb + dff + 4 * n) = acc[ai][0][m][n]; *(f32x4*)(sb + 2 * dff + 4 * n) = acc[ai][1][m][n]; } }
.LBB0_1249:
	v_cndmask_b32_e64 v201, v152, v136, s[38:39]
	s_waitcnt lgkmcnt(0)
	v_cndmask_b32_e64 v172, v152, v172, s[40:41]
	v_cndmask_b32_e64 v173, v153, v173, s[40:41]
	v_mov_b32_dpp v202, v201 row_ror:15 row_mask:0xf bank_mask:0xf bound_ctrl:1
	v_cndmask_b32_e64 v201, v153, v137, s[38:39]
	v_mov_b32_dpp v172, v172 row_ror:1 row_mask:0xf bank_mask:0xf bound_ctrl:1
	v_mov_b32_dpp v173, v173 row_ror:1 row_mask:0xf bank_mask:0xf bound_ctrl:1
	v_mov_b32_dpp v203, v201 row_ror:15 row_mask:0xf bank_mask:0xf bound_ctrl:1
	v_pk_fma_f32 v[202:203], v[100:101], v[202:203], v[104:105]
	v_cndmask_b32_e64 v201, v154, v138, s[38:39]
	v_pk_fma_f32 v[202:203], v[96:97], v[152:153], v[202:203]
	v_cndmask_b32_e64 v174, v154, v174, s[40:41]
	v_pk_fma_f32 v[172:173], v[92:93], v[172:173], v[202:203]
	v_mov_b32_dpp v202, v201 row_ror:15 row_mask:0xf bank_mask:0xf bound_ctrl:1
	v_cndmask_b32_e64 v201, v155, v139, s[38:39]
	v_cndmask_b32_e64 v175, v155, v175, s[40:41]
	v_mov_b32_dpp v174, v174 row_ror:1 row_mask:0xf bank_mask:0xf bound_ctrl:1
	v_mov_b32_dpp v203, v201 row_ror:15 row_mask:0xf bank_mask:0xf bound_ctrl:1
	v_pk_fma_f32 v[202:203], v[102:103], v[202:203], v[106:107]
	v_mov_b32_dpp v175, v175 row_ror:1 row_mask:0xf bank_mask:0xf bound_ctrl:1
	v_pk_fma_f32 v[202:203], v[98:99], v[154:155], v[202:203]
	v_cndmask_b32_e64 v201, v148, v132, s[38:39]
	v_pk_fma_f32 v[174:175], v[94:95], v[174:175], v[202:203]
	v_cndmask_b32_e64 v176, v148, v176, s[40:41]
	v_mov_b32_dpp v202, v201 row_ror:15 row_mask:0xf bank_mask:0xf bound_ctrl:1
	v_cndmask_b32_e64 v201, v149, v133, s[38:39]
	v_cndmask_b32_e64 v177, v149, v177, s[40:41]
	v_mov_b32_dpp v176, v176 row_ror:1 row_mask:0xf bank_mask:0xf bound_ctrl:1
	v_mov_b32_dpp v203, v201 row_ror:15 row_mask:0xf bank_mask:0xf bound_ctrl:1
	v_pk_fma_f32 v[202:203], v[84:85], v[202:203], v[88:89]
	v_mov_b32_dpp v177, v177 row_ror:1 row_mask:0xf bank_mask:0xf bound_ctrl:1
	v_pk_fma_f32 v[202:203], v[76:77], v[148:149], v[202:203]
	v_cndmask_b32_e64 v201, v150, v134, s[38:39]
	v_pk_fma_f32 v[176:177], v[72:73], v[176:177], v[202:203]
	v_cndmask_b32_e64 v178, v150, v178, s[40:41]
	v_mov_b32_dpp v202, v201 row_ror:15 row_mask:0xf bank_mask:0xf bound_ctrl:1
	v_cndmask_b32_e64 v201, v151, v135, s[38:39]
	v_cndmask_b32_e64 v179, v151, v179, s[40:41]
	s_lshl_b32 s8, s10, 1
	v_mov_b32_dpp v203, v201 row_ror:15 row_mask:0xf bank_mask:0xf bound_ctrl:1
	v_pk_fma_f32 v[202:203], v[86:87], v[202:203], v[90:91]
	v_mov_b32_dpp v178, v178 row_ror:1 row_mask:0xf bank_mask:0xf bound_ctrl:1
	v_mov_b32_dpp v179, v179 row_ror:1 row_mask:0xf bank_mask:0xf bound_ctrl:1
	v_pk_fma_f32 v[202:203], v[78:79], v[150:151], v[202:203]
	s_mul_hi_i32 s13, s8, 0x10800
	v_pk_fma_f32 v[178:179], v[74:75], v[178:179], v[202:203]
	s_mul_i32 s18, s8, 0x10800
	s_and_saveexec_b64 s[72:73], s[42:43]
	s_cbranch_execz .LBB0_1251
	s_add_u32 s20, s90, s18
	s_addc_u32 s21, s91, s13
	v_lshl_add_u64 v[202:203], v[190:191], 2, s[20:21]
	v_add_co_u32_e32 v204, vcc, 0x5000, v202
	global_store_dwordx4 v[202:203], v[172:175], off
	s_nop 0
	v_addc_co_u32_e32 v205, vcc, 0, v203, vcc
	v_add_co_u32_e32 v206, vcc, 0xb000, v202
	global_store_dwordx4 v[204:205], v[160:163], off offset:2048
	s_nop 0
	v_addc_co_u32_e32 v207, vcc, 0, v203, vcc
	global_store_dwordx4 v[206:207], v[152:155], off
	global_store_dwordx4 v[202:203], v[176:179], off offset:16
	global_store_dwordx4 v[204:205], v[156:159], off offset:2064
	global_store_dwordx4 v[206:207], v[148:151], off offset:16
